# speedup vs baseline: 1.0305x; 1.0059x over previous
.LBB0_22:
	v_and_b32_e32 v6, 0x1800, v11
	v_add_u32_e32 v6, 0xfffff800, v6
	v_cmp_gt_u32_e32 vcc, s0, v11
	s_nop 1
	v_cndmask_b32_e64 v6, v6, 0, vcc
	v_cndmask_b32_e32 v13, v5, v8, vcc
	v_cndmask_b32_e32 v12, v9, v10, vcc
	v_and_or_b32 v6, v11, s1, v6
	v_lshl_add_u64 v[12:13], v[6:7], 2, v[12:13]
	global_load_dword v6, v[12:13], off
	v_add_u32_e32 v12, 0x200, v11
	v_cmp_lt_u32_e32 vcc, s2, v11
	v_mov_b32_e32 v11, v12
	s_or_b64 s[4:5], vcc, s[4:5]
	s_waitcnt vmcnt(0)
	v_mul_f32_e32 v12, 0xbfb8aa3b, v6
	v_exp_f32_e32 v12, v12
	s_nop 0
	v_add_f32_e32 v12, 1.0, v12
	v_div_scale_f32 v13, s[6:7], v12, v12, v6
	v_rcp_f32_e32 v14, v13
	v_div_scale_f32 v15, vcc, v6, v12, v6
	v_fma_f32 v16, -v13, v14, 1.0
	v_fmac_f32_e32 v14, v16, v14
	v_mul_f32_e32 v16, v15, v14
	v_fma_f32 v17, -v13, v16, v15
	v_fmac_f32_e32 v16, v17, v14
	v_fma_f32 v13, -v13, v16, v15
	v_div_fmas_f32 v13, v13, v14, v16
	v_div_fixup_f32 v6, v13, v12, v6
	ds_write_b32 v3, v6
	v_add_u32_e32 v3, 0x800, v3
	s_andn2_b64 exec, exec, s[4:5]
	s_cbranch_execnz .LBB0_22
	s_or_b64 exec, exec, s[4:5]
	v_readfirstlane_b32 s1, v4
	v_readfirstlane_b32 s0, v2
	s_waitcnt lgkmcnt(0)
	v_writelane_b32 v255, s1, 6
	s_barrier
	v_readlane_b32 s1, v255, 0
	s_cmpk_gt_i32 s1, 0x2885
	s_cbranch_scc1 .LBB0_89
	v_add_u32_e32 v2, 0x200, v190
	v_lshrrev_b32_e32 v76, 6, v2
	v_add_u32_e32 v2, 0x600, v190
	v_lshrrev_b32_e32 v78, 6, v2
	v_add_u32_e32 v2, 0xa00, v190
	v_lshrrev_b32_e32 v80, 6, v2
	v_add_u32_e32 v2, 0xe00, v190
	v_lshrrev_b32_e32 v63, 6, v190
	v_lshrrev_b32_e32 v82, 6, v2
	s_movk_i32 s1, 0x404
	v_mov_b32_e32 v2, 0x4040
	v_mad_u32_u24 v31, v63, s1, v2
	v_mov_b32_e32 v2, 0x8080
	v_mad_u32_u24 v33, v63, s1, v2
	v_mov_b32_e32 v2, 0xc0c0
	v_mad_u32_u24 v35, v63, s1, v2
	v_lshlrev_b32_e32 v2, 3, v190
	v_lshrrev_b32_e32 v83, 3, v190
	v_and_b32_e32 v2, 56, v2
	v_mul_u32_u24_e32 v4, 0x404, v2
	v_lshlrev_b32_e32 v5, 2, v83
	v_add3_u32 v84, 0, v4, v5
	v_and_b32_e32 v4, 15, v190
	v_and_b32_e32 v6, 31, v190
	s_mov_b32 s4, 0xbd000000
	v_cvt_f32_ubyte0_e32 v5, v4
	v_cvt_f32_ubyte0_e32 v4, v6
	s_mov_b32 s5, 0xbd800000
	v_pk_mul_f32 v[4:5], v[4:5], s[4:5]
	v_mov_b32_e32 v20, 0x461c4000
	v_cmp_eq_f32_e32 vcc, 0, v5
	s_mov_b32 s1, 0x3f2aaaab
	v_mov_b32_e32 v22, 0x3e91f4c4
	v_cndmask_b32_e64 v16, v20, 1.0, vcc
	v_frexp_mant_f32_e32 v6, v16
	v_cmp_gt_f32_e64 s[4:5], s1, v6
	s_mov_b32 s2, 0x3f317218
	v_mov_b32_e32 v23, 0x3ecccdef
	v_cndmask_b32_e64 v7, 1.0, 2.0, s[4:5]
	v_mul_f32_e32 v6, v6, v7
	v_add_f32_e32 v9, 1.0, v6
	v_rcp_f32_e32 v14, v9
	v_add_f32_e32 v7, -1.0, v9
	v_sub_f32_e32 v11, v6, v7
	v_add_f32_e32 v7, -1.0, v6
	v_mul_f32_e32 v15, v7, v14
	v_mul_f32_e32 v8, v9, v15
	v_fma_f32 v10, v15, v9, -v8
	v_fmac_f32_e32 v10, v15, v11
	v_add_f32_e32 v6, v8, v10
	v_sub_f32_e32 v9, v7, v6
	v_pk_add_f32 v[12:13], v[6:7], v[8:9] neg_lo:[0,1] neg_hi:[0,1]
	v_mov_b32_e32 v11, v6
	v_pk_add_f32 v[6:7], v[12:13], v[10:11] neg_lo:[0,1] neg_hi:[0,1]
	s_mov_b32 s8, 0x3fb8aa3b
	v_add_f32_e32 v6, v6, v7
	v_add_f32_e32 v6, v9, v6
	v_mul_f32_e32 v7, v14, v6
	v_add_f32_e32 v6, v15, v7
	v_sub_f32_e32 v8, v6, v15
	v_sub_f32_e32 v17, v7, v8
	v_mul_f32_e32 v7, v6, v6
	v_fma_f32 v9, v6, v6, -v7
	v_add_f32_e32 v8, v17, v17
	v_fmac_f32_e32 v9, v6, v8
	v_add_f32_e32 v8, v7, v9
	v_fmamk_f32 v10, v8, 0x3e76c4e1, v22
	v_fmaak_f32 v10, v8, v10, 0x3ecccdef
	v_sub_f32_e32 v7, v8, v7
	v_sub_f32_e32 v18, v9, v7
	v_mul_f32_e32 v7, v8, v10
	v_fma_f32 v9, v8, v10, -v7
	v_fmac_f32_e32 v9, v18, v10
	v_add_f32_e32 v10, v7, v9
	v_add_f32_e32 v11, 0x3f2aaaaa, v10
	v_sub_f32_e32 v7, v10, v7
	v_sub_f32_e32 v7, v9, v7
	v_add_f32_e32 v9, 0xbf2aaaaa, v11
	v_add_f32_e32 v7, 0x31739010, v7
	v_sub_f32_e32 v9, v10, v9
	v_pk_mul_f32 v[12:13], v[6:7], v[8:9]
	v_pk_add_f32 v[14:15], v[6:7], v[8:9]
	v_fma_f32 v10, v8, v6, -v12
	v_fmac_f32_e32 v10, v8, v17
	v_mov_b32_e32 v13, v15
	v_fmac_f32_e32 v10, v18, v6
	v_pk_add_f32 v[8:9], v[12:13], v[10:11]
	v_ldexp_f32 v18, v17, 1
	v_sub_f32_e32 v7, v8, v12
	v_sub_f32_e32 v7, v10, v7
	v_sub_f32_e32 v10, v11, v9
	v_add_f32_e32 v13, v15, v10
	v_pk_mul_f32 v[10:11], v[8:9], v[8:9] op_sel:[0,1] op_sel_hi:[1,0]
	v_cvt_f64_f32_e32 v[14:15], v16
	v_frexp_exp_i32_f64_e32 v11, v[14:15]
	v_subbrev_co_u32_e64 v11, s[4:5], 0, v11, s[4:5]
	v_cvt_f32_i32_e32 v11, v11
	v_fma_f32 v12, v8, v9, -v10
	v_fmac_f32_e32 v12, v8, v13
	v_fmac_f32_e32 v12, v7, v9
	v_mul_f32_e32 v8, 0x3f317218, v11
	v_fma_f32 v14, v11, s2, -v8
	v_fmac_f32_e32 v14, 0xb102e308, v11
	v_ldexp_f32 v15, v6, 1
	v_add_f32_e32 v9, v10, v12
	v_pk_add_f32 v[6:7], v[8:9], v[14:15]
	v_mov_b32_e32 v16, v9
	v_mov_b32_e32 v17, v7
	v_mov_b32_e32 v11, v15
	v_pk_add_f32 v[10:11], v[16:17], v[10:11] neg_lo:[0,1] neg_hi:[0,1]
	v_mov_b32_e32 v13, v9
	v_pk_add_f32 v[10:11], v[12:13], v[10:11] neg_lo:[0,1] neg_hi:[0,1]
	v_mov_b32_e32 v15, v6
	v_add_f32_e32 v9, v18, v10
	v_add_f32_e32 v9, v9, v11
	v_pk_add_f32 v[10:11], v[6:7], v[8:9] neg_lo:[0,1] neg_hi:[0,1]
	v_pk_add_f32 v[12:13], v[6:7], v[8:9]
	v_mov_b32_e32 v8, v9
	v_mov_b32_e32 v11, v13
	v_pk_add_f32 v[16:17], v[14:15], v[10:11] neg_lo:[0,1] neg_hi:[0,1]
	v_pk_add_f32 v[10:11], v[14:15], v[10:11]
	v_mov_b32_e32 v9, v6
	v_pk_add_f32 v[14:15], v[10:11], v[6:7] op_sel:[1,0] op_sel_hi:[0,1] neg_lo:[0,1] neg_hi:[0,1]
	v_pk_add_f32 v[18:19], v[12:13], v[14:15] op_sel_hi:[1,0] neg_lo:[0,1] neg_hi:[0,1]
	v_mov_b32_e32 v10, v13
	v_pk_mov_b32 v[12:13], v[6:7], v[14:15] op_sel:[1,0]
	v_mov_b32_e32 v18, v16
	v_pk_add_f32 v[12:13], v[10:11], v[12:13] neg_lo:[0,1] neg_hi:[0,1]
	v_cmp_eq_f32_e64 s[4:5], 0, v4
	v_pk_add_f32 v[6:7], v[8:9], v[12:13] neg_lo:[0,1] neg_hi:[0,1]
	v_mov_b32_e32 v17, v11
	v_pk_add_f32 v[8:9], v[18:19], v[6:7]
	v_cndmask_b32_e64 v7, v20, 1.0, s[4:5]
	v_frexp_mant_f32_e32 v10, v7
	v_cmp_gt_f32_e64 s[6:7], s1, v10
	s_mov_b32 s1, 0x7f800000
	s_mov_b32 s9, 0xc2ce8ed0
	v_cndmask_b32_e64 v12, 1.0, 2.0, s[6:7]
	v_mul_f32_e32 v10, v10, v12
	v_add_f32_e32 v12, 1.0, v10
	v_rcp_f32_e32 v24, v12
	v_add_f32_e32 v13, -1.0, v12
	v_sub_f32_e32 v15, v10, v13
	v_add_f32_e32 v13, -1.0, v10
	v_mul_f32_e32 v10, v13, v24
	v_mul_f32_e32 v14, v12, v10
	v_fma_f32 v18, v10, v12, -v14
	v_fmac_f32_e32 v18, v10, v15
	v_add_f32_e32 v12, v14, v18
	v_sub_f32_e32 v15, v13, v12
	v_pk_add_f32 v[20:21], v[12:13], v[14:15] neg_lo:[0,1] neg_hi:[0,1]
	v_mov_b32_e32 v19, v12
	v_pk_add_f32 v[12:13], v[20:21], v[18:19] neg_lo:[0,1] neg_hi:[0,1]
	s_movk_i32 s10, 0x204
	v_add_f32_e32 v12, v12, v13
	v_add_f32_e32 v12, v15, v12
	v_mul_f32_e32 v13, v24, v12
	v_add_f32_e32 v12, v10, v13
	v_sub_f32_e32 v10, v12, v10
	v_sub_f32_e32 v10, v13, v10
	v_mul_f32_e32 v13, v12, v12
	v_fma_f32 v15, v12, v12, -v13
	v_add_f32_e32 v14, v10, v10
	v_fmac_f32_e32 v15, v12, v14
	v_add_f32_e32 v14, v13, v15
	v_fmac_f32_e32 v22, 0x3e76c4e1, v14
	v_fmac_f32_e32 v23, v14, v22
	v_sub_f32_e32 v13, v14, v13
	v_sub_f32_e32 v24, v15, v13
	v_mul_f32_e32 v13, v14, v23
	v_fma_f32 v15, v14, v23, -v13
	v_fmac_f32_e32 v15, v24, v23
	v_add_f32_e32 v18, v13, v15
	v_add_f32_e32 v19, 0x3f2aaaaa, v18
	v_sub_f32_e32 v13, v18, v13
	v_sub_f32_e32 v13, v15, v13
	v_add_f32_e32 v15, 0xbf2aaaaa, v19
	v_add_f32_e32 v13, 0x31739010, v13
	v_sub_f32_e32 v15, v18, v15
	v_pk_mul_f32 v[20:21], v[12:13], v[14:15]
	v_pk_add_f32 v[22:23], v[12:13], v[14:15]
	v_fma_f32 v18, v14, v12, -v20
	v_fmac_f32_e32 v18, v14, v10
	v_mov_b32_e32 v21, v23
	v_fmac_f32_e32 v18, v24, v12
	v_pk_add_f32 v[14:15], v[20:21], v[18:19]
	v_and_b32_e32 v62, 0xfc, v1
	v_sub_f32_e32 v13, v14, v20
	v_cvt_f64_f32_e32 v[20:21], v7
	v_frexp_exp_i32_f64_e32 v7, v[20:21]
	v_subbrev_co_u32_e64 v7, s[6:7], 0, v7, s[6:7]
	v_cvt_f32_i32_e32 v7, v7
	v_sub_f32_e32 v13, v18, v13
	v_sub_f32_e32 v18, v19, v15
	v_add_f32_e32 v22, v23, v18
	v_pk_mul_f32 v[18:19], v[14:15], v[14:15] op_sel:[0,1] op_sel_hi:[1,0]
	v_ldexp_f32 v23, v12, 1
	v_fma_f32 v20, v14, v15, -v18
	v_fmac_f32_e32 v20, v14, v22
	v_mul_f32_e32 v14, 0x3f317218, v7
	v_fmac_f32_e32 v20, v13, v15
	v_fma_f32 v22, v7, s2, -v14
	v_fmac_f32_e32 v22, 0xb102e308, v7
	v_add_f32_e32 v15, v18, v20
	v_pk_add_f32 v[12:13], v[14:15], v[22:23]
	v_mov_b32_e32 v24, v15
	v_mov_b32_e32 v25, v13
	v_mov_b32_e32 v19, v23
	v_pk_add_f32 v[18:19], v[24:25], v[18:19] neg_lo:[0,1] neg_hi:[0,1]
	v_mov_b32_e32 v21, v15
	v_ldexp_f32 v7, v10, 1
	v_pk_add_f32 v[18:19], v[20:21], v[18:19] neg_lo:[0,1] neg_hi:[0,1]
	v_mov_b32_e32 v23, v12
	v_add_f32_e32 v7, v7, v18
	v_add_f32_e32 v15, v7, v19
	v_pk_add_f32 v[18:19], v[12:13], v[14:15] neg_lo:[0,1] neg_hi:[0,1]
	v_pk_add_f32 v[20:21], v[12:13], v[14:15]
	v_mov_b32_e32 v14, v15
	v_mov_b32_e32 v19, v21
	v_pk_add_f32 v[24:25], v[22:23], v[18:19] neg_lo:[0,1] neg_hi:[0,1]
	v_pk_add_f32 v[18:19], v[22:23], v[18:19]
	v_mov_b32_e32 v15, v12
	v_pk_add_f32 v[22:23], v[18:19], v[12:13] op_sel:[1,0] op_sel_hi:[0,1] neg_lo:[0,1] neg_hi:[0,1]
	v_pk_add_f32 v[26:27], v[20:21], v[22:23] op_sel_hi:[1,0] neg_lo:[0,1] neg_hi:[0,1]
	v_mov_b32_e32 v18, v21
	v_pk_mov_b32 v[20:21], v[12:13], v[22:23] op_sel:[1,0]
	v_mov_b32_e32 v26, v24
	v_pk_add_f32 v[20:21], v[18:19], v[20:21] neg_lo:[0,1] neg_hi:[0,1]
	v_mov_b32_e32 v23, v9
	v_pk_add_f32 v[12:13], v[14:15], v[20:21] neg_lo:[0,1] neg_hi:[0,1]
	v_mov_b32_e32 v21, v8
	v_pk_add_f32 v[14:15], v[26:27], v[12:13]
	v_mov_b32_e32 v10, v19
	v_mov_b32_e32 v20, v14
	v_mov_b32_e32 v22, v15
	v_pk_add_f32 v[22:23], v[20:21], v[22:23]
	v_mov_b32_e32 v25, v19
	v_pk_add_f32 v[10:11], v[10:11], v[22:23]
	v_mov_b32_e32 v7, v23
	v_mov_b32_e32 v9, v11
	v_mov_b32_e32 v15, v10
	v_pk_add_f32 v[8:9], v[8:9], v[16:17] neg_lo:[0,1] neg_hi:[0,1]
	v_pk_add_f32 v[14:15], v[14:15], v[24:25] neg_lo:[0,1] neg_hi:[0,1]
	v_mov_b32_e32 v19, v8
	v_mov_b32_e32 v18, v14
	v_mov_b32_e32 v13, v22
	v_pk_add_f32 v[6:7], v[6:7], v[8:9] neg_lo:[0,1] neg_hi:[0,1]
	v_pk_add_f32 v[8:9], v[20:21], v[18:19] neg_lo:[0,1] neg_hi:[0,1]
	v_mov_b32_e32 v25, v16
	v_pk_add_f32 v[12:13], v[12:13], v[14:15] neg_lo:[0,1] neg_hi:[0,1]
	v_pk_add_f32 v[8:9], v[24:25], v[8:9] neg_lo:[0,1] neg_hi:[0,1]
	v_mov_b32_e32 v14, v12
	v_mov_b32_e32 v15, v6
	v_pk_add_f32 v[8:9], v[14:15], v[8:9]
	v_mov_b32_e32 v6, v13
	v_pk_add_f32 v[6:7], v[8:9], v[6:7]
	s_mov_b32 s2, 0x42b17218
	v_pk_add_f32 v[8:9], v[10:11], v[6:7]
	v_lshlrev_b32_e32 v28, 2, v62
	v_pk_add_f32 v[10:11], v[8:9], v[10:11] neg_lo:[0,1] neg_hi:[0,1]
	v_lshl_add_u32 v89, v63, 10, 0
	v_pk_add_f32 v[6:7], v[6:7], v[10:11] neg_lo:[0,1] neg_hi:[0,1]
	v_pk_mul_f32 v[10:11], v[4:5], v[8:9]
	v_mov_b32_e32 v65, 0
	v_pk_fma_f32 v[8:9], v[4:5], v[8:9], v[10:11] neg_lo:[0,0,1] neg_hi:[0,0,1]
	v_add_u32_e32 v3, 0, v28
	v_pk_fma_f32 v[6:7], v[4:5], v[6:7], v[8:9]
	v_mul_u32_u24_e32 v29, 0x404, v63
	v_pk_add_f32 v[8:9], v[10:11], v[6:7]
	v_mul_u32_u24_e32 v30, 0x404, v76
	v_pk_add_f32 v[12:13], v[8:9], v[10:11] neg_lo:[0,1] neg_hi:[0,1]
	v_mul_u32_u24_e32 v32, 0x404, v78
	v_pk_add_f32 v[6:7], v[6:7], v[12:13] neg_lo:[0,1] neg_hi:[0,1]
	v_mov_b32_e32 v12, 0x204
	v_cmp_class_f32_e64 s[6:7], v10, v12
	v_mul_u32_u24_e32 v34, 0x404, v80
	v_mul_u32_u24_e32 v36, 0x404, v82
	v_cndmask_b32_e64 v8, v8, v10, s[6:7]
	v_cmp_class_f32_e64 s[6:7], v11, v12
	v_mov_b32_e32 v10, 0x37000000
	s_add_u32 s46, s36, 0x2dc48000
	v_cndmask_b32_e64 v9, v9, v11, s[6:7]
	v_cmp_eq_f32_e64 s[6:7], s2, v9
	v_or_b32_e32 v77, 16, v63
	v_or_b32_e32 v79, 32, v63
	v_cndmask_b32_e64 v11, 0, v10, s[6:7]
	v_sub_f32_e32 v12, v9, v11
	v_mul_f32_e32 v13, 0x3fb8aa3b, v12
	v_fma_f32 v14, v12, s8, -v13
	v_rndne_f32_e32 v15, v13
	v_fmac_f32_e32 v14, 0x32a5705f, v12
	v_sub_f32_e32 v13, v13, v15
	v_add_f32_e32 v13, v13, v14
	v_exp_f32_e32 v13, v13
	v_cvt_i32_f32_e32 v14, v15
	v_cmp_neq_f32_e64 s[6:7], |v9|, s1
	v_or_b32_e32 v81, 48, v63
	s_mov_b32 s41, 0
	v_cndmask_b32_e64 v7, 0, v7, s[6:7]
	v_ldexp_f32 v9, v13, v14
	v_cmp_ngt_f32_e64 s[6:7], s9, v12
	v_add_f32_e32 v7, v11, v7
	v_mov_b32_e32 v11, 0x7f800000
	v_cndmask_b32_e64 v9, 0, v9, s[6:7]
	v_cmp_nlt_f32_e64 s[6:7], s2, v12
	v_or_b32_e32 v85, 0x80, v83
	v_or_b32_e32 v86, 0xffff4000, v190
	v_cndmask_b32_e64 v9, v11, v9, s[6:7]
	v_fma_f32 v7, v9, v7, v9
	v_cmp_class_f32_e64 s[6:7], v9, s10
	v_lshlrev_b32_e32 v66, 8, v63
	v_mov_b32_e32 v67, v65
	v_cndmask_b32_e64 v7, v7, v9, s[6:7]
	v_cmp_neq_f32_e64 s[6:7], v5, |v5|
	s_addc_u32 s47, s37, 0
	v_add_u32_e32 v91, 0xfffffe00, v190
	v_cndmask_b32_e64 v9, v11, 0, s[6:7]
	v_cndmask_b32_e64 v9, v9, 1.0, vcc
	v_cmp_eq_f32_e32 vcc, s2, v8
	v_cmp_class_f32_e64 s[6:7], v5, s10
	s_mov_b32 s33, 0xf400000
	v_cndmask_b32_e32 v5, 0, v10, vcc
	v_cndmask_b32_e64 v87, |v7|, v9, s[6:7]
	v_sub_f32_e32 v7, v8, v5
	v_mul_f32_e32 v9, 0x3fb8aa3b, v7
	v_fma_f32 v10, v7, s8, -v9
	v_rndne_f32_e32 v12, v9
	v_fmac_f32_e32 v10, 0x32a5705f, v7
	v_sub_f32_e32 v9, v9, v12
	v_add_f32_e32 v9, v9, v10
	v_exp_f32_e32 v9, v9
	v_cvt_i32_f32_e32 v10, v12
	v_cmp_neq_f32_e64 vcc, |v8|, s1
	v_cmp_neq_f32_e64 s[6:7], v4, |v4|
	s_movk_i32 s1, 0x300
	v_cndmask_b32_e32 v6, 0, v6, vcc
	v_add_f32_e32 v5, v5, v6
	v_ldexp_f32 v6, v9, v10
	v_cmp_ngt_f32_e32 vcc, s9, v7
	s_mov_b32 s8, 0x31850000
	s_mov_b32 s9, 0x30bd0000
	v_cndmask_b32_e32 v6, 0, v6, vcc
	v_cmp_nlt_f32_e32 vcc, s2, v7
	s_mov_b32 s2, 0xc000
	s_mov_b32 s54, 0xb400000
	v_cndmask_b32_e32 v6, v11, v6, vcc
	v_fma_f32 v5, v6, v5, v6
	v_cmp_class_f32_e64 vcc, v6, s10
	s_mov_b32 s55, 0x8c00000
	s_movk_i32 s56, 0xa8
	v_cndmask_b32_e32 v5, v5, v6, vcc
	v_cndmask_b32_e64 v6, v11, 0, s[6:7]
	v_readlane_b32 s6, v255, 1
	v_cndmask_b32_e64 v6, v6, 1.0, s[4:5]
	v_cmp_class_f32_e64 s[4:5], v4, s10
	v_lshlrev_b32_e32 v4, 11, v63
	v_readlane_b32 s7, v255, 2
	v_cndmask_b32_e64 v88, |v5|, v6, s[4:5]
	v_add3_u32 v90, v89, v4, v28
	s_load_dwordx8 s[16:23], s[6:7], 0x10
	s_load_dwordx2 s[42:43], s[6:7], 0xc8
	s_load_dwordx4 s[24:27], s[6:7], 0xb8
	s_load_dwordx4 s[28:31], s[6:7], 0x40
	s_load_dwordx2 s[44:45], s[6:7], 0x60
	v_lshrrev_b32_e32 v4, 8, v190
	v_mov_b32_e32 v6, 2
	v_mul_hi_u32_u24_e32 v5, 0xc000, v4
	v_mul_u32_u24_e32 v4, 0xc000, v4
	v_lshlrev_b32_sdwa v6, v6, v190 dst_sel:DWORD dst_unused:UNUSED_PAD src0_sel:DWORD src1_sel:BYTE_0
	v_or_b32_e32 v4, v4, v6
	v_lshl_add_u64 v[4:5], s[36:37], 0, v[4:5]
	s_mov_b64 s[6:7], 0x2dc00000
	v_lshl_add_u64 v[68:69], v[4:5], 0, s[6:7]
	s_movk_i32 s6, 0xc00
	v_and_or_b32 v4, v1, s6, v6
	v_add_u32_e32 v4, 0, v4
	v_cmp_gt_u32_e64 s[4:5], s1, v190
	s_movk_i32 s1, 0xff
	v_add_u32_e32 v92, 0x6000, v4
	s_mov_b32 s57, 0x7800000
	v_add_u32_e32 v93, v3, v29
	v_add_u32_e32 v94, v3, v30
	v_add_u32_e32 v95, v3, v31
	v_add_u32_e32 v96, v3, v32
	v_add_u32_e32 v97, v3, v33
	v_add_u32_e32 v98, v3, v34
	v_add_u32_e32 v99, v3, v35
	v_add_u32_e32 v100, v3, v36
	v_lshlrev_b32_e32 v70, 1, v2
	s_mov_b32 s58, 0x2ff50000
	s_mov_b32 s59, 0x2f2d0000
	s_movk_i32 s60, 0x7ff
	s_brev_b32 s61, 18
	s_mov_b32 s62, 0xfe5163ab
	s_mov_b32 s63, 0x3c439041
	s_mov_b32 s64, 0xdb629599
	s_mov_b32 s65, 0xf534ddc0
	s_mov_b32 s66, 0xfc2757d1
	s_mov_b32 s67, 0x4e441529
	s_mov_b32 s68, 0xa2f9836e
	s_mov_b32 s69, 0x3fc90fda
	s_mov_b32 s70, 0x3f22f983
	s_mov_b32 s71, 0xbfc90fda
	v_mov_b32_e32 v101, 0x3c0881c4
	v_mov_b32_e32 v102, 0xbab64f3b
	s_brev_b32 s72, 1
	s_movk_i32 s73, 0x1f8
	s_mov_b32 s74, 0x18000
	s_mov_b32 s75, 0x24000
	s_mov_b32 s76, 0x30000
	s_mov_b32 s77, 0x3c000
	s_mov_b32 s78, 0x48000
	s_mov_b32 s79, 0x54000
	s_mov_b32 s80, 0x60000
	s_mov_b32 s81, 0x6c000
	s_mov_b32 s82, 0x78000
	s_mov_b32 s83, 0x84000
	s_mov_b32 s84, 0x90000
	s_mov_b32 s85, 0x9c000
	s_mov_b32 s86, 0xa8000
	s_mov_b32 s87, 0xb4000
	s_mov_b64 s[48:49], 0x18000
	v_not_b32_e32 v103, 63
	v_not_b32_e32 v104, 31
	v_mov_b32_e32 v105, 0x7fc00000
	v_readlane_b32 s88, v255, 0
	s_mov_b32 s32, 0
	s_movk_i32 s90, 0x2886
	s_cmpk_eq_i32 s3, 0x100
	s_cselect_b32 s93, 1, 0
	s_cmpk_lt_i32 s88, 96
	s_cselect_b32 s94, 1, 0
	s_and_b32 s94, s94, s93
	s_cmp_eq_u32 s94, 1
	s_cselect_b32 s90, 6656, s90
	s_branch .LBB0_27

.LBB0_26:
	s_cmp_eq_u32 s32, 0
	s_cbranch_scc0 .Lprep_left_next
	s_add_i32 s88, s88, s3
	s_cmp_lt_i32 s88, s90
	s_cbranch_scc1 .LBB0_27
	s_cmp_eq_u32 s93, 1
	s_cbranch_scc0 .LBB0_89
	v_readlane_b32 s89, v255, 0
	s_cmpk_lt_i32 s89, 96
	s_cbranch_scc1 .LBB0_89
	s_mov_b32 s32, 1
	s_sub_i32 s89, s89, 96
	s_branch .Lprep_left_item
.Lprep_left_next:
	s_addk_i32 s89, 0xa0
.Lprep_left_item:
	s_cmpk_lt_i32 s89, 1440
	s_cbranch_scc0 .LBB0_89
	s_mul_i32 s91, s89, 0x2ab
	s_lshr_b32 s91, s91, 16
	s_mul_i32 s92, s91, 96
	s_sub_i32 s92, s89, s92
	s_add_i32 s91, s91, 26
	s_lshl_b32 s91, s91, 8
	s_add_i32 s88, s91, s92
